# P1: column-tile types reordered inside a panel (zt and silu tiles alternate) to even out per-workgroup epilogue cost
# speedup vs baseline: 1.0032x; 1.0009x over previous
.Lp01_j:
	s_mul_i32 s67, s66, 0x2e9
	s_lshr_b32 s67, s67, 13
	s_mul_i32 s68, s67, 11
	s_sub_i32 s68, s66, s68
	s_lshl_b32 s69, s68, 2
	s_mov_b32 s70, 0x74653210
	s_mov_b32 s71, 0xa89
	s_lshr_b64 s[70:71], s[70:71], s69
	s_and_b32 s68, s70, 15
	s_lshl_b32 s67, s67, 3
	s_add_i32 s67, s67, s61
	s_mul_i32 s33, s67, 11
	s_add_i32 s33, s33, s68
	s_add_i32 s60, s60, 1
